# grid barrier: waiters poll the cross-XCD arrival counter directly (no separate release generation), one atomic round trip less after the last arrival
# baseline (speedup 1.0000x reference)
.LBB0_181:
	s_or_b64 exec, exec, s[8:9]
	v_cvt_f32_u32_e32 v5, v3
	s_waitcnt vmcnt(0)
	v_readfirstlane_b32 s0, v4
	v_sub_u32_e32 v4, 0, v3
	v_rcp_iflag_f32_e32 v5, v5
	v_add_u32_e32 v6, s0, v0
	v_mul_f32_e32 v5, 0x4f7ffffe, v5
	v_cvt_u32_f32_e32 v5, v5
	v_mul_lo_u32 v0, v4, v5
	v_mul_hi_u32 v0, v5, v0
	v_add_u32_e32 v0, v5, v0
	v_mul_hi_u32 v0, v6, v0
	v_mul_lo_u32 v4, v0, v3
	v_sub_u32_e32 v4, v6, v4
	v_add_u32_e32 v5, 1, v0
	v_cmp_ge_u32_e32 vcc, v4, v3
	s_nop 1
	v_cndmask_b32_e32 v0, v0, v5, vcc
	v_sub_u32_e32 v5, v4, v3
	v_cndmask_b32_e32 v4, v4, v5, vcc
	v_add_u32_e32 v5, 1, v0
	v_cmp_ge_u32_e32 vcc, v4, v3
	v_add_u32_e32 v4, 1, v6
	s_nop 0
	v_cndmask_b32_e32 v0, v0, v5, vcc
	v_mul_lo_u32 v5, v3, v0
	v_add_u32_e32 v3, v5, v3
	v_cmp_ne_u32_e32 vcc, v4, v3
	s_and_saveexec_b64 s[0:1], vcc
	s_xor_b64 s[8:9], exec, s[0:1]
	s_cbranch_execz .LBB0_195
	s_waitcnt lgkmcnt(0)
	s_add_u32 s0, s96, 0x3400
	s_addc_u32 s1, s97, 0
	v_mul_lo_u32 v4, v0, v2
	v_add_u32_e32 v0, v4, v2
	global_load_dword v2, v1, s[0:1] sc1
	s_waitcnt vmcnt(0)
	v_cmp_lt_u32_e32 vcc, v2, v0
	s_and_saveexec_b64 s[10:11], vcc
	s_cbranch_execz .LBB0_194
	s_mov_b32 s19, 1
	s_mov_b64 s[12:13], 0
	s_branch .LBB0_185

.LBB0_187:
	global_load_dword v2, v1, s[0:1] sc1
	s_add_i32 s19, s19, 1
	s_mov_b64 s[20:21], -1
	s_waitcnt vmcnt(0)
	v_cmp_ge_u32_e32 vcc, v2, v0
	s_orn2_b64 s[16:17], vcc, exec
	s_branch .LBB0_184

.LBB0_198:
	s_or_b64 exec, exec, s[8:9]
	s_waitcnt vmcnt(0)
	v_readfirstlane_b32 s0, v3
	v_sub_u32_e32 v4, 0, v2
	v_readlane_b32 s8, v252, 50
	v_add_u32_e32 v3, s0, v0
	v_cvt_f32_u32_e32 v0, v2
	v_readlane_b32 s9, v252, 51
	s_mov_b64 s[0:1], 0
	v_rcp_iflag_f32_e32 v0, v0
	s_nop 0
	v_mul_f32_e32 v0, 0x4f7ffffe, v0
	v_cvt_u32_f32_e32 v0, v0
	v_mul_lo_u32 v4, v4, v0
	v_mul_hi_u32 v4, v0, v4
	v_add_u32_e32 v0, v0, v4
	v_mul_hi_u32 v0, v3, v0
	v_mul_lo_u32 v4, v0, v2
	v_sub_u32_e32 v4, v3, v4
	v_cmp_ge_u32_e32 vcc, v4, v2
	v_add_u32_e32 v5, 1, v0
	v_add_u32_e32 v3, 1, v3
	v_cndmask_b32_e32 v0, v0, v5, vcc
	v_sub_u32_e32 v5, v4, v2
	v_cndmask_b32_e32 v4, v4, v5, vcc
	v_cmp_ge_u32_e32 vcc, v4, v2
	v_add_u32_e32 v4, 1, v0
	s_nop 0
	v_cndmask_b32_e32 v0, v0, v4, vcc
	v_mul_lo_u32 v4, v2, v0
	v_add_u32_e32 v2, v4, v2
	v_cmp_ne_u32_e32 vcc, v3, v2
	v_mov_b32_e32 v4, v2
	v_mov_b64_e32 v[2:3], s[8:9]
	s_and_saveexec_b64 s[8:9], vcc
	s_cbranch_execz .LBB0_210
	v_readlane_b32 s0, v252, 48
	v_readlane_b32 s1, v252, 49
	s_nop 4
	global_load_dword v2, v1, s[0:1] sc1
	s_mov_b64 s[0:1], 0
	s_waitcnt vmcnt(0)
	v_cmp_lt_u32_e32 vcc, v2, v4
	s_and_saveexec_b64 s[10:11], vcc
	s_cbranch_execz .LBB0_209
	s_mov_b32 s19, 1
	s_branch .LBB0_202

.LBB0_204:
	v_readlane_b32 s14, v252, 48
	v_readlane_b32 s15, v252, 49
	s_add_i32 s19, s19, 1
	s_mov_b64 s[16:17], -1
	s_nop 2
	global_load_dword v2, v1, s[14:15] sc1
	s_waitcnt vmcnt(0)
	v_cmp_ge_u32_e32 vcc, v2, v4
	s_orn2_b64 s[14:15], vcc, exec
	s_branch .LBB0_201

.LBB0_859:
	s_or_b64 exec, exec, s[8:9]
	v_cvt_f32_u32_e32 v5, v3
	s_waitcnt vmcnt(0)
	v_readfirstlane_b32 s0, v4
	v_sub_u32_e32 v4, 0, v3
	v_rcp_iflag_f32_e32 v5, v5
	v_add_u32_e32 v6, s0, v0
	v_mul_f32_e32 v5, 0x4f7ffffe, v5
	v_cvt_u32_f32_e32 v5, v5
	v_mul_lo_u32 v0, v4, v5
	v_mul_hi_u32 v0, v5, v0
	v_add_u32_e32 v0, v5, v0
	v_mul_hi_u32 v0, v6, v0
	v_mul_lo_u32 v4, v0, v3
	v_sub_u32_e32 v4, v6, v4
	v_add_u32_e32 v5, 1, v0
	v_cmp_ge_u32_e32 vcc, v4, v3
	s_nop 1
	v_cndmask_b32_e32 v0, v0, v5, vcc
	v_sub_u32_e32 v5, v4, v3
	v_cndmask_b32_e32 v4, v4, v5, vcc
	v_add_u32_e32 v5, 1, v0
	v_cmp_ge_u32_e32 vcc, v4, v3
	v_add_u32_e32 v4, 1, v6
	s_nop 0
	v_cndmask_b32_e32 v0, v0, v5, vcc
	v_mul_lo_u32 v5, v3, v0
	v_add_u32_e32 v3, v5, v3
	v_cmp_ne_u32_e32 vcc, v4, v3
	s_and_saveexec_b64 s[0:1], vcc
	s_xor_b64 s[8:9], exec, s[0:1]
	s_cbranch_execz .LBB0_873
	s_waitcnt lgkmcnt(0)
	s_add_u32 s0, s96, 0x3400
	s_addc_u32 s1, s97, 0
	v_mul_lo_u32 v4, v0, v2
	v_add_u32_e32 v0, v4, v2
	global_load_dword v2, v1, s[0:1] sc1
	s_waitcnt vmcnt(0)
	v_cmp_lt_u32_e32 vcc, v2, v0
	s_and_saveexec_b64 s[10:11], vcc
	s_cbranch_execz .LBB0_872
	s_mov_b32 s26, 1
	s_mov_b64 s[12:13], 0
	s_branch .LBB0_863

.LBB0_865:
	global_load_dword v2, v1, s[0:1] sc1
	s_add_i32 s26, s26, 1
	s_mov_b64 s[20:21], -1
	s_waitcnt vmcnt(0)
	v_cmp_ge_u32_e32 vcc, v2, v0
	s_orn2_b64 s[16:17], vcc, exec
	s_branch .LBB0_862

.LBB0_876:
	s_or_b64 exec, exec, s[8:9]
	s_waitcnt vmcnt(0)
	v_readfirstlane_b32 s0, v3
	v_sub_u32_e32 v4, 0, v2
	v_readlane_b32 s8, v252, 50
	v_add_u32_e32 v3, s0, v0
	v_cvt_f32_u32_e32 v0, v2
	v_readlane_b32 s9, v252, 51
	s_mov_b64 s[0:1], 0
	v_rcp_iflag_f32_e32 v0, v0
	s_nop 0
	v_mul_f32_e32 v0, 0x4f7ffffe, v0
	v_cvt_u32_f32_e32 v0, v0
	v_mul_lo_u32 v4, v4, v0
	v_mul_hi_u32 v4, v0, v4
	v_add_u32_e32 v0, v0, v4
	v_mul_hi_u32 v0, v3, v0
	v_mul_lo_u32 v4, v0, v2
	v_sub_u32_e32 v4, v3, v4
	v_cmp_ge_u32_e32 vcc, v4, v2
	v_add_u32_e32 v5, 1, v0
	v_add_u32_e32 v3, 1, v3
	v_cndmask_b32_e32 v0, v0, v5, vcc
	v_sub_u32_e32 v5, v4, v2
	v_cndmask_b32_e32 v4, v4, v5, vcc
	v_cmp_ge_u32_e32 vcc, v4, v2
	v_add_u32_e32 v4, 1, v0
	s_nop 0
	v_cndmask_b32_e32 v0, v0, v4, vcc
	v_mul_lo_u32 v4, v2, v0
	v_add_u32_e32 v2, v4, v2
	v_cmp_ne_u32_e32 vcc, v3, v2
	v_mov_b32_e32 v4, v2
	v_mov_b64_e32 v[2:3], s[8:9]
	s_and_saveexec_b64 s[8:9], vcc
	s_cbranch_execz .LBB0_888
	v_readlane_b32 s0, v252, 48
	v_readlane_b32 s1, v252, 49
	s_nop 4
	global_load_dword v2, v1, s[0:1] sc1
	s_mov_b64 s[0:1], 0
	s_waitcnt vmcnt(0)
	v_cmp_lt_u32_e32 vcc, v2, v4
	s_and_saveexec_b64 s[10:11], vcc
	s_cbranch_execz .LBB0_887
	s_mov_b32 s24, 1
	s_branch .LBB0_880

.LBB0_882:
	v_readlane_b32 s14, v252, 48
	v_readlane_b32 s15, v252, 49
	s_add_i32 s24, s24, 1
	s_mov_b64 s[16:17], -1
	s_nop 2
	global_load_dword v2, v1, s[14:15] sc1
	s_waitcnt vmcnt(0)
	v_cmp_ge_u32_e32 vcc, v2, v4
	s_orn2_b64 s[14:15], vcc, exec
	s_branch .LBB0_879
